# v10 + attention hot-path row sums as packed pair adds (30 v_pk_add_f32 instead of 60 v_add_f32)
# speedup vs baseline: 1.0029x; 1.0029x over previous
; #define AT2_EXP(S0, S1) _Pragma("unroll") for (int i = 0; i < 16; ++i) { const float p0 = __builtin_amdgcn_exp2f(S0[i]), p1 = __builtin_amdgcn_exp2f(S1[i]); S0[i] = p0; S1[i] = p1; rsum += p0; rsum += p1; }
; __device__ __forceinline__ void attn_tile2(LAS unsigned char* BA, LAS unsigned char* BB, unsigned kf_off, unsigned vf_off, const bf16x8 (&qf)[4], f32x16& O0, f32x16& O1, float& mrun, float& lrun, bool on) {
;     ...
;     float rsum = 0.f;
;     ...
;     AT2_EXP(sa0, sa1)
;     AT2_PV(sa0, sa1, BA)
;     AT2_EXP(sb0, sb1)
;     AT2_PV(sb0, sb1, BB)
;     ...
;     lrun += rsum;
.LBB0_394:
	v_exp_f32_e32 v9, v82
	v_exp_f32_e32 v11, v83
	v_exp_f32_e32 v13, v84
	v_exp_f32_e32 v15, v85
	v_exp_f32_e32 v17, v86
	v_exp_f32_e32 v83, v87
	v_exp_f32_e32 v85, v88
	v_exp_f32_e32 v87, v89
	v_add_u32_e32 v8, s1, v205
	v_exp_f32_e32 v10, v98
	v_exp_f32_e32 v12, v99
	v_exp_f32_e32 v14, v100
	v_exp_f32_e32 v16, v101
	v_exp_f32_e32 v82, v102
	v_exp_f32_e32 v84, v103
	v_exp_f32_e32 v86, v104
	v_exp_f32_e32 v89, v90
	v_exp_f32_e32 v90, v106
	v_exp_f32_e32 v98, v107
	v_exp_f32_e32 v99, v108
	v_exp_f32_e32 v100, v109
	v_exp_f32_e32 v101, v110
	v_exp_f32_e32 v102, v111
	v_exp_f32_e32 v103, v112
	v_exp_f32_e32 v104, v113
	ds_read_b128 v[106:109], v8 offset:13824
	ds_read_b128 v[110:113], v8 offset:9216
	ds_read_b128 v[114:117], v8 offset:9248
	v_cvt_pk_bf16_f32 v4, v9, v11
	v_cvt_pk_bf16_f32 v5, v13, v15
	v_cvt_pk_bf16_f32 v6, v17, v83
	v_cvt_pk_bf16_f32 v7, v85, v87
	v_exp_f32_e32 v91, v91
	v_exp_f32_e32 v92, v92
	s_waitcnt lgkmcnt(1)
	v_mfma_f32_32x32x16_bf16 v[18:33], v[110:113], v[4:7], v[18:33]
	v_exp_f32_e32 v93, v93
	v_exp_f32_e32 v94, v94
	v_exp_f32_e32 v95, v95
	v_exp_f32_e32 v96, v96
	v_exp_f32_e32 v97, v97
	v_mfma_f32_32x32x16_bf16 v[34:49], v[106:109], v[4:7], v[34:49]
	ds_read_b128 v[106:109], v8 offset:13856
	v_cvt_pk_bf16_f32 v4, v89, v91
	v_cvt_pk_bf16_f32 v5, v92, v93
	v_cvt_pk_bf16_f32 v6, v94, v95
	v_cvt_pk_bf16_f32 v7, v96, v97
	v_pk_add_f32 v[238:239], v[10:11], v[12:13]
	s_waitcnt lgkmcnt(1)
	v_mfma_f32_32x32x16_bf16 v[18:33], v[114:117], v[4:7], v[18:33]
	v_pk_add_f32 v[238:239], v[238:239], v[14:15]
	v_exp_f32_e32 v88, v105
	v_pk_add_f32 v[238:239], v[238:239], v[16:17]
	v_pk_add_f32 v[238:239], v[238:239], v[82:83]
	s_waitcnt lgkmcnt(0)
	v_mfma_f32_32x32x16_bf16 v[34:49], v[106:109], v[4:7], v[34:49]
	ds_read_b128 v[106:109], v8 offset:9280
	ds_read_b128 v[110:113], v8 offset:13888
	v_cvt_pk_bf16_f32 v4, v10, v12
	v_cvt_pk_bf16_f32 v5, v14, v16
	v_cvt_pk_bf16_f32 v6, v82, v84
	v_cvt_pk_bf16_f32 v7, v86, v88
	v_pk_add_f32 v[238:239], v[238:239], v[84:85]
	s_waitcnt lgkmcnt(1)
	v_mfma_f32_32x32x16_bf16 v[18:33], v[106:109], v[4:7], v[18:33]
	v_pk_add_f32 v[238:239], v[238:239], v[86:87]
	v_pk_add_f32 v[238:239], v[238:239], v[88:89]
	v_pk_add_f32 v[238:239], v[238:239], v[90:91]
	s_waitcnt lgkmcnt(0)
	v_mfma_f32_32x32x16_bf16 v[34:49], v[110:113], v[4:7], v[34:49]
	ds_read_b128 v[106:109], v8 offset:9312
	ds_read_b128 v[110:113], v8 offset:13920
	v_cvt_pk_bf16_f32 v4, v90, v98
	v_cvt_pk_bf16_f32 v5, v99, v100
	v_cvt_pk_bf16_f32 v6, v101, v102
	v_cvt_pk_bf16_f32 v7, v103, v104
	v_pk_add_f32 v[238:239], v[238:239], v[98:99]
	v_pk_add_f32 v[238:239], v[238:239], v[92:93]
	s_waitcnt lgkmcnt(1)
	v_mfma_f32_32x32x16_bf16 v[18:33], v[106:109], v[4:7], v[18:33]
	v_exp_f32_e32 v66, v66
	v_exp_f32_e32 v67, v67
	v_exp_f32_e32 v68, v68
	v_exp_f32_e32 v69, v69
	v_exp_f32_e32 v70, v70
	v_exp_f32_e32 v71, v71
	v_exp_f32_e32 v72, v72
	v_exp_f32_e32 v73, v73
	s_waitcnt lgkmcnt(0)
	v_mfma_f32_32x32x16_bf16 v[34:49], v[110:113], v[4:7], v[34:49]
	v_exp_f32_e32 v105, v50
	v_exp_f32_e32 v106, v51
	v_exp_f32_e32 v107, v52
	v_exp_f32_e32 v108, v53
	v_exp_f32_e32 v109, v54
	v_exp_f32_e32 v110, v55
	v_exp_f32_e32 v111, v56
	v_exp_f32_e32 v112, v57
	ds_read_b128 v[50:53], v8 offset:27648
	ds_read_b128 v[54:57], v8 offset:32256
	v_pk_add_f32 v[238:239], v[238:239], v[100:101]
	v_pk_add_f32 v[238:239], v[238:239], v[94:95]
	v_cvt_pk_bf16_f32 v4, v66, v67
	v_cvt_pk_bf16_f32 v5, v68, v69
	v_cvt_pk_bf16_f32 v6, v70, v71
	v_cvt_pk_bf16_f32 v7, v72, v73
	v_pk_add_f32 v[238:239], v[238:239], v[102:103]
	s_waitcnt lgkmcnt(1)
	v_mfma_f32_32x32x16_bf16 v[18:33], v[50:53], v[4:7], v[18:33]
	v_pk_add_f32 v[238:239], v[238:239], v[96:97]
	v_add_f32_e32 v9, v104, v9
	v_exp_f32_e32 v74, v74
	v_exp_f32_e32 v75, v75
	v_exp_f32_e32 v76, v76
	v_exp_f32_e32 v77, v77
	v_exp_f32_e32 v78, v78
	v_exp_f32_e32 v79, v79
	v_exp_f32_e32 v80, v80
	v_exp_f32_e32 v81, v81
	s_waitcnt lgkmcnt(0)
	v_mfma_f32_32x32x16_bf16 v[34:49], v[54:57], v[4:7], v[34:49]
	ds_read_b128 v[50:53], v8 offset:27680
	ds_read_b128 v[54:57], v8 offset:32288
	v_add_f32_e32 v9, v105, v9
	v_pk_add_f32 v[238:239], v[238:239], v[66:67]
	v_cvt_pk_bf16_f32 v4, v74, v75
	v_cvt_pk_bf16_f32 v5, v76, v77
	v_cvt_pk_bf16_f32 v6, v78, v79
	v_cvt_pk_bf16_f32 v7, v80, v81
	v_pk_add_f32 v[238:239], v[238:239], v[106:107]
	s_waitcnt lgkmcnt(1)
	v_mfma_f32_32x32x16_bf16 v[18:33], v[50:53], v[4:7], v[18:33]
	v_pk_add_f32 v[238:239], v[238:239], v[68:69]
	v_pk_add_f32 v[238:239], v[238:239], v[108:109]
	v_pk_add_f32 v[238:239], v[238:239], v[70:71]
	s_waitcnt lgkmcnt(0)
	v_mfma_f32_32x32x16_bf16 v[34:49], v[54:57], v[4:7], v[34:49]
	ds_read_b128 v[50:53], v8 offset:27712
	ds_read_b128 v[54:57], v8 offset:32320
	v_cvt_pk_bf16_f32 v4, v105, v106
	v_cvt_pk_bf16_f32 v5, v107, v108
	v_cvt_pk_bf16_f32 v6, v109, v110
	v_cvt_pk_bf16_f32 v7, v111, v112
	v_pk_add_f32 v[238:239], v[238:239], v[110:111]
	v_pk_add_f32 v[238:239], v[238:239], v[72:73]
	s_waitcnt lgkmcnt(1)
	v_mfma_f32_32x32x16_bf16 v[18:33], v[50:53], v[4:7], v[18:33]
	v_exp_f32_e32 v51, v58
	v_exp_f32_e32 v52, v59
	v_add_f32_e32 v9, v112, v9
	v_exp_f32_e32 v53, v60
	v_pk_add_f32 v[238:239], v[238:239], v[74:75]
	s_waitcnt lgkmcnt(0)
	v_mfma_f32_32x32x16_bf16 v[34:49], v[54:57], v[4:7], v[34:49]
	v_exp_f32_e32 v54, v61
	v_exp_f32_e32 v55, v62
	v_exp_f32_e32 v56, v63
	v_exp_f32_e32 v57, v64
	v_exp_f32_e32 v50, v65
	ds_read_b128 v[10:13], v8 offset:27744
	ds_read_b128 v[14:17], v8 offset:32352
	v_pk_add_f32 v[238:239], v[238:239], v[52:53]
	v_pk_add_f32 v[238:239], v[238:239], v[76:77]
	v_cvt_pk_bf16_f32 v4, v51, v52
	v_cvt_pk_bf16_f32 v5, v53, v54
	v_cvt_pk_bf16_f32 v6, v55, v56
	v_cvt_pk_bf16_f32 v7, v57, v50
	v_pk_add_f32 v[238:239], v[238:239], v[54:55]
	s_waitcnt lgkmcnt(1)
	v_mfma_f32_32x32x16_bf16 v[18:33], v[10:13], v[4:7], v[18:33]
	v_pk_add_f32 v[238:239], v[238:239], v[78:79]
	v_pk_add_f32 v[238:239], v[238:239], v[56:57]
	v_pk_add_f32 v[238:239], v[238:239], v[80:81]
	s_waitcnt lgkmcnt(0)
	v_mfma_f32_32x32x16_bf16 v[34:49], v[14:17], v[4:7], v[34:49]
	v_pk_add_f32 v[238:239], v[238:239], v[50:51]
	v_add_f32_e32 v9, v238, v9
	v_add_f32_e32 v4, v239, v9
	v_add_f32_e32 v214, v214, v4
